# v11 + attention loop control rotated: ring/tile counters, LDS offset and branch flags formed in front of the barrier
# baseline (speedup 1.0000x reference)
.LBB0_530:
	s_add_i32 s10, s0, 1
	s_cmp_lg_u32 s0, 2
	s_cselect_b32 s0, s10, 0
	s_add_i32 s10, s7, 1
	s_cmp_lg_u32 s7, 2
	s_cselect_b32 s7, s10, 0
	s_add_i32 s33, s33, 1
	s_add_i32 s86, s86, 64
	s_mul_i32 s100, s0, 0xa000
	s_add_i32 s10, s33, 2
	s_cmp_ge_u32 s10, s28
	s_cselect_b64 s[22:23], -1, 0
	s_cmp_gt_i32 s33, s21
	s_cselect_b64 s[34:35], -1, 0
	s_and_b64 vcc, exec, s[34:35]
	s_cmp_eq_u32 s28, s33
	s_barrier
.Lat1_dispatch:
	s_cbranch_scc1 .LBB0_539
	s_cbranch_vccnz .Lat1_skip
	s_and_b64 vcc, exec, s[22:23]
	s_cbranch_vccnz .Lat1_nodma
	s_setprio 3
	v_add_u32_e32 v14, s100, v0
	v_add_u32_e32 v15, s100, v212
	v_add_u32_e32 v176, s100, v213
	v_add_u32_e32 v177, s100, v219
	ds_read_b128 v[144:147], v14 offset:0
	ds_read_b128 v[148:151], v15 offset:0
	ds_read_b128 v[152:155], v176 offset:0
	ds_read_b128 v[156:159], v177 offset:0
	ds_read_b128 v[160:163], v14 offset:8192
	ds_read_b128 v[164:167], v15 offset:8192
	ds_read_b128 v[168:171], v176 offset:8192
	ds_read_b128 v[172:175], v177 offset:8192
	ds_read_b128 v[2:5], v14 offset:16384
	ds_read_b128 v[6:9], v15 offset:16384
	ds_read_b128 v[10:13], v176 offset:16384
	ds_read_b128 v[238:241], v177 offset:16384
	s_waitcnt lgkmcnt(8)
	v_mfma_f32_32x32x16_bf16 v[80:95], v[144:147], v[132:135], 0
	v_mfma_f32_32x32x16_bf16 v[80:95], v[148:151], v[128:131], v[80:95]
	v_mfma_f32_32x32x16_bf16 v[80:95], v[152:155], v[124:127], v[80:95]
	v_mfma_f32_32x32x16_bf16 v[80:95], v[156:159], v[120:123], v[80:95]
	ds_read_b128 v[144:147], v14 offset:4096
	ds_read_b128 v[148:151], v15 offset:4096
	ds_read_b128 v[152:155], v176 offset:4096
	ds_read_b128 v[156:159], v177 offset:4096
	s_waitcnt lgkmcnt(8)
	v_mfma_f32_32x32x16_bf16 v[80:95], v[160:163], v[116:119], v[80:95]
	v_mfma_f32_32x32x16_bf16 v[80:95], v[164:167], v[112:115], v[80:95]
	v_mfma_f32_32x32x16_bf16 v[80:95], v[168:171], v[108:111], v[80:95]
	v_mfma_f32_32x32x16_bf16 v[80:95], v[172:175], v[104:107], v[80:95]
	ds_read_b128 v[160:163], v14 offset:12288
	ds_read_b128 v[164:167], v15 offset:12288
	ds_read_b128 v[168:171], v176 offset:12288
	ds_read_b128 v[172:175], v177 offset:12288
	s_waitcnt lgkmcnt(8)
	v_mfma_f32_32x32x16_bf16 v[80:95], v[2:5], v[100:103], v[80:95]
	v_mfma_f32_32x32x16_bf16 v[80:95], v[6:9], v[140:143], v[80:95]
	v_mfma_f32_32x32x16_bf16 v[80:95], v[10:13], v[96:99], v[80:95]
	v_mfma_f32_32x32x16_bf16 v[80:95], v[238:241], v[136:139], v[80:95]
	s_setprio 2
	ds_read_b128 v[2:5], v14 offset:20480
	ds_read_b128 v[6:9], v15 offset:20480
	ds_read_b128 v[10:13], v176 offset:20480
	ds_read_b128 v[238:241], v177 offset:20480
	s_waitcnt lgkmcnt(8)
	v_mfma_f32_32x32x16_bf16 v[184:199], v[144:147], v[132:135], 0
	v_mfma_f32_32x32x16_bf16 v[184:199], v[148:151], v[128:131], v[184:199]
	v_mfma_f32_32x32x16_bf16 v[184:199], v[152:155], v[124:127], v[184:199]
	v_mfma_f32_32x32x16_bf16 v[184:199], v[156:159], v[120:123], v[184:199]
	ds_read_b128 v[144:147], v14 offset:24576
	ds_read_b128 v[148:151], v14 offset:28672
	ds_read_b128 v[152:155], v14 offset:32768
	ds_read_b128 v[156:159], v14 offset:36864
	s_waitcnt lgkmcnt(8)
	v_mfma_f32_32x32x16_bf16 v[184:199], v[160:163], v[116:119], v[184:199]
	v_med3_f32 v80, v80, s4, v236
	v_exp_f32_e32 v80, v80
	v_med3_f32 v81, v81, s4, v236
	v_exp_f32_e32 v81, v81
	v_mfma_f32_32x32x16_bf16 v[184:199], v[164:167], v[112:115], v[184:199]
	v_med3_f32 v82, v82, s4, v236
	v_exp_f32_e32 v82, v82
	v_med3_f32 v83, v83, s4, v236
	v_exp_f32_e32 v83, v83
	v_mfma_f32_32x32x16_bf16 v[184:199], v[168:171], v[108:111], v[184:199]
	v_med3_f32 v84, v84, s4, v236
	v_exp_f32_e32 v84, v84
	v_med3_f32 v85, v85, s4, v236
	v_exp_f32_e32 v85, v85
	v_mfma_f32_32x32x16_bf16 v[184:199], v[172:175], v[104:107], v[184:199]
	v_med3_f32 v86, v86, s4, v236
	v_exp_f32_e32 v86, v86
	v_med3_f32 v87, v87, s4, v236
	v_exp_f32_e32 v87, v87
	ds_read_b128 v[160:163], v15 offset:24576
	ds_read_b128 v[164:167], v15 offset:28672
	ds_read_b128 v[168:171], v15 offset:32768
	ds_read_b128 v[172:175], v15 offset:36864
	s_waitcnt lgkmcnt(8)
	v_mfma_f32_32x32x16_bf16 v[184:199], v[2:5], v[100:103], v[184:199]
	v_med3_f32 v88, v88, s4, v236
	v_exp_f32_e32 v88, v88
	v_med3_f32 v89, v89, s4, v236
	v_exp_f32_e32 v89, v89
	v_add_f32_e32 v200, v80, v81
	v_add_f32_e32 v200, v200, v82
	v_mfma_f32_32x32x16_bf16 v[184:199], v[6:9], v[140:143], v[184:199]
	v_med3_f32 v90, v90, s4, v236
	v_exp_f32_e32 v90, v90
	v_med3_f32 v91, v91, s4, v236
	v_exp_f32_e32 v91, v91
	v_add_f32_e32 v200, v200, v83
	v_add_f32_e32 v200, v200, v84
	v_mfma_f32_32x32x16_bf16 v[184:199], v[10:13], v[96:99], v[184:199]
	v_med3_f32 v92, v92, s4, v236
	v_exp_f32_e32 v92, v92
	v_med3_f32 v93, v93, s4, v236
	v_exp_f32_e32 v93, v93
	v_add_f32_e32 v200, v200, v85
	v_add_f32_e32 v200, v200, v86
	v_mfma_f32_32x32x16_bf16 v[184:199], v[238:241], v[136:139], v[184:199]
	v_med3_f32 v94, v94, s4, v236
	v_exp_f32_e32 v94, v94
	v_med3_f32 v95, v95, s4, v236
	v_exp_f32_e32 v95, v95
	v_add_f32_e32 v200, v200, v87
	s_setprio 1
	ds_read_b128 v[2:5], v176 offset:24576
	ds_read_b128 v[6:9], v176 offset:28672
	ds_read_b128 v[10:13], v176 offset:32768
	ds_read_b128 v[238:241], v176 offset:36864
	v_cvt_pk_bf16_f32 v80, v80, v81
	v_cvt_pk_bf16_f32 v81, v82, v83
	v_cvt_pk_bf16_f32 v82, v84, v85
	v_cvt_pk_bf16_f32 v83, v86, v87
	v_add_f32_e32 v200, v200, v88
	v_add_f32_e32 v200, v200, v89
	s_waitcnt lgkmcnt(8)
	v_mfma_f32_32x32x16_bf16 v[64:79], v[80:83], v[144:147], v[64:79]
	v_med3_f32 v184, v184, s4, v236
	v_exp_f32_e32 v184, v184
	v_med3_f32 v185, v185, s4, v236
	v_exp_f32_e32 v185, v185
	v_add_f32_e32 v200, v200, v90
	v_add_f32_e32 v200, v200, v91
	v_mfma_f32_32x32x16_bf16 v[48:63], v[80:83], v[148:151], v[48:63]
	v_med3_f32 v186, v186, s4, v236
	v_exp_f32_e32 v186, v186
	v_med3_f32 v187, v187, s4, v236
	v_exp_f32_e32 v187, v187
	v_add_f32_e32 v200, v200, v92
	v_add_f32_e32 v200, v200, v93
	v_mfma_f32_32x32x16_bf16 v[32:47], v[80:83], v[152:155], v[32:47]
	v_med3_f32 v188, v188, s4, v236
	v_exp_f32_e32 v188, v188
	v_med3_f32 v189, v189, s4, v236
	v_exp_f32_e32 v189, v189
	v_add_f32_e32 v200, v200, v94
	v_add_f32_e32 v200, v200, v95
	v_mfma_f32_32x32x16_bf16 v[16:31], v[80:83], v[156:159], v[16:31]
	v_med3_f32 v190, v190, s4, v236
	v_exp_f32_e32 v190, v190
	v_med3_f32 v191, v191, s4, v236
	v_exp_f32_e32 v191, v191
	v_cvt_pk_bf16_f32 v84, v88, v89
	v_cvt_pk_bf16_f32 v85, v90, v91
	v_cvt_pk_bf16_f32 v86, v92, v93
	v_cvt_pk_bf16_f32 v87, v94, v95
	ds_read_b128 v[144:147], v177 offset:24576
	ds_read_b128 v[148:151], v177 offset:28672
	ds_read_b128 v[152:155], v177 offset:32768
	ds_read_b128 v[156:159], v177 offset:36864
	s_waitcnt lgkmcnt(8)
	v_mfma_f32_32x32x16_bf16 v[64:79], v[84:87], v[160:163], v[64:79]
	v_med3_f32 v192, v192, s4, v236
	v_exp_f32_e32 v192, v192
	v_med3_f32 v193, v193, s4, v236
	v_exp_f32_e32 v193, v193
	v_add_f32_e32 v201, v184, v185
	v_add_f32_e32 v201, v201, v186
	v_mfma_f32_32x32x16_bf16 v[48:63], v[84:87], v[164:167], v[48:63]
	v_med3_f32 v194, v194, s4, v236
	v_exp_f32_e32 v194, v194
	v_med3_f32 v195, v195, s4, v236
	v_exp_f32_e32 v195, v195
	v_add_f32_e32 v201, v201, v187
	v_add_f32_e32 v201, v201, v188
	v_mfma_f32_32x32x16_bf16 v[32:47], v[84:87], v[168:171], v[32:47]
	v_med3_f32 v196, v196, s4, v236
	v_exp_f32_e32 v196, v196
	v_med3_f32 v197, v197, s4, v236
	v_exp_f32_e32 v197, v197
	v_add_f32_e32 v201, v201, v189
	v_mfma_f32_32x32x16_bf16 v[16:31], v[84:87], v[172:175], v[16:31]
	v_med3_f32 v198, v198, s4, v236
	v_exp_f32_e32 v198, v198
	v_med3_f32 v199, v199, s4, v236
	v_exp_f32_e32 v199, v199
	v_add_f32_e32 v201, v201, v190
	v_cvt_pk_bf16_f32 v184, v184, v185
	v_cvt_pk_bf16_f32 v185, v186, v187
	v_cvt_pk_bf16_f32 v186, v188, v189
	v_cvt_pk_bf16_f32 v187, v190, v191
	v_add_f32_e32 v201, v201, v191
	s_setprio 0
	s_waitcnt lgkmcnt(4)
	v_mfma_f32_32x32x16_bf16 v[64:79], v[184:187], v[2:5], v[64:79]
	v_mad_u64_u32 v[202:203], s[10:11], s86, v228, v[180:181]
	s_mul_i32 s10, s7, 0xa000
	s_add_i32 s10, s9, s10
	s_mov_b32 m0, s10
	v_lshl_add_u64 v[204:205], v[202:203], 0, s[94:95]
	global_load_lds_dwordx4 v[202:203], off
	v_add_f32_e32 v201, v201, v192
	v_add_f32_e32 v201, v201, v193
	v_add_f32_e32 v201, v201, v194
	v_mfma_f32_32x32x16_bf16 v[48:63], v[184:187], v[6:9], v[48:63]
	s_add_i32 m0, s10, 0x2000
	v_lshl_add_u64 v[202:203], v[202:203], 0, s[96:97]
	global_load_lds_dwordx4 v[204:205], off
	v_add_f32_e32 v201, v201, v195
	v_add_f32_e32 v201, v201, v196
	v_add_f32_e32 v201, v201, v197
	v_mfma_f32_32x32x16_bf16 v[32:47], v[184:187], v[10:13], v[32:47]
	s_add_i32 m0, s10, 0x4000
	s_nop 0
	global_load_lds_dwordx4 v[202:203], off
	v_lshl_add_u64 v[202:203], s[86:87], 1, v[182:183]
	s_add_i32 m0, s10, 0x6000
	v_add_f32_e32 v201, v201, v198
	v_add_f32_e32 v201, v201, v199
	v_cvt_pk_bf16_f32 v188, v192, v193
	v_cvt_pk_bf16_f32 v189, v194, v195
	v_cvt_pk_bf16_f32 v190, v196, v197
	v_cvt_pk_bf16_f32 v191, v198, v199
	v_mfma_f32_32x32x16_bf16 v[16:31], v[184:187], v[238:241], v[16:31]
	global_load_lds_dwordx4 v[202:203], off
	v_lshl_add_u64 v[202:203], v[202:203], 0, s[92:93]
	s_add_i32 m0, s10, 0x8000
	v_add_f32_e32 v200, v200, v201
	v_add_f32_e32 v218, v218, v200
	s_waitcnt lgkmcnt(0)
	v_mfma_f32_32x32x16_bf16 v[64:79], v[188:191], v[144:147], v[64:79]
	global_load_lds_dwordx4 v[202:203], off
	v_mfma_f32_32x32x16_bf16 v[48:63], v[188:191], v[148:151], v[48:63]
	v_mfma_f32_32x32x16_bf16 v[32:47], v[188:191], v[152:155], v[32:47]
	v_mfma_f32_32x32x16_bf16 v[16:31], v[188:191], v[156:159], v[16:31]
	s_waitcnt vmcnt(5) lgkmcnt(0)
	s_branch .LBB0_530
.LBB0_531:
	s_mul_i32 s100, s0, 0xa000
	s_add_i32 s10, s33, 2
	s_cmp_ge_u32 s10, s28
	s_cselect_b64 s[22:23], -1, 0
	s_cmp_gt_i32 s33, s21
	s_cselect_b64 s[34:35], -1, 0
	s_and_b64 vcc, exec, s[34:35]
	s_cmp_eq_u32 s28, s33
	s_branch .Lat1_dispatch
.Lat1_nodma:
	s_setprio 3
	v_add_u32_e32 v14, s100, v0
	v_add_u32_e32 v15, s100, v212
	v_add_u32_e32 v176, s100, v213
	v_add_u32_e32 v177, s100, v219
	ds_read_b128 v[144:147], v14 offset:0
	ds_read_b128 v[148:151], v15 offset:0
	ds_read_b128 v[152:155], v176 offset:0
	ds_read_b128 v[156:159], v177 offset:0
	ds_read_b128 v[160:163], v14 offset:8192
	ds_read_b128 v[164:167], v15 offset:8192
	ds_read_b128 v[168:171], v176 offset:8192
	ds_read_b128 v[172:175], v177 offset:8192
	ds_read_b128 v[2:5], v14 offset:16384
	ds_read_b128 v[6:9], v15 offset:16384
	ds_read_b128 v[10:13], v176 offset:16384
	ds_read_b128 v[238:241], v177 offset:16384
	s_waitcnt lgkmcnt(8)
	v_mfma_f32_32x32x16_bf16 v[80:95], v[144:147], v[132:135], 0
	v_mfma_f32_32x32x16_bf16 v[80:95], v[148:151], v[128:131], v[80:95]
	v_mfma_f32_32x32x16_bf16 v[80:95], v[152:155], v[124:127], v[80:95]
	v_mfma_f32_32x32x16_bf16 v[80:95], v[156:159], v[120:123], v[80:95]
	ds_read_b128 v[144:147], v14 offset:4096
	ds_read_b128 v[148:151], v15 offset:4096
	ds_read_b128 v[152:155], v176 offset:4096
	ds_read_b128 v[156:159], v177 offset:4096
	s_waitcnt lgkmcnt(8)
	v_mfma_f32_32x32x16_bf16 v[80:95], v[160:163], v[116:119], v[80:95]
	v_mfma_f32_32x32x16_bf16 v[80:95], v[164:167], v[112:115], v[80:95]
	v_mfma_f32_32x32x16_bf16 v[80:95], v[168:171], v[108:111], v[80:95]
	v_mfma_f32_32x32x16_bf16 v[80:95], v[172:175], v[104:107], v[80:95]
	ds_read_b128 v[160:163], v14 offset:12288
	ds_read_b128 v[164:167], v15 offset:12288
	ds_read_b128 v[168:171], v176 offset:12288
	ds_read_b128 v[172:175], v177 offset:12288
	s_waitcnt lgkmcnt(8)
	v_mfma_f32_32x32x16_bf16 v[80:95], v[2:5], v[100:103], v[80:95]
	v_mfma_f32_32x32x16_bf16 v[80:95], v[6:9], v[140:143], v[80:95]
	v_mfma_f32_32x32x16_bf16 v[80:95], v[10:13], v[96:99], v[80:95]
	v_mfma_f32_32x32x16_bf16 v[80:95], v[238:241], v[136:139], v[80:95]
	s_setprio 2
	ds_read_b128 v[2:5], v14 offset:20480
	ds_read_b128 v[6:9], v15 offset:20480
	ds_read_b128 v[10:13], v176 offset:20480
	ds_read_b128 v[238:241], v177 offset:20480
	s_waitcnt lgkmcnt(8)
	v_mfma_f32_32x32x16_bf16 v[184:199], v[144:147], v[132:135], 0
	v_mfma_f32_32x32x16_bf16 v[184:199], v[148:151], v[128:131], v[184:199]
	v_mfma_f32_32x32x16_bf16 v[184:199], v[152:155], v[124:127], v[184:199]
	v_mfma_f32_32x32x16_bf16 v[184:199], v[156:159], v[120:123], v[184:199]
	ds_read_b128 v[144:147], v14 offset:24576
	ds_read_b128 v[148:151], v14 offset:28672
	ds_read_b128 v[152:155], v14 offset:32768
	ds_read_b128 v[156:159], v14 offset:36864
	s_waitcnt lgkmcnt(8)
	v_mfma_f32_32x32x16_bf16 v[184:199], v[160:163], v[116:119], v[184:199]
	v_med3_f32 v80, v80, s4, v236
	v_exp_f32_e32 v80, v80
	v_med3_f32 v81, v81, s4, v236
	v_exp_f32_e32 v81, v81
	v_mfma_f32_32x32x16_bf16 v[184:199], v[164:167], v[112:115], v[184:199]
	v_med3_f32 v82, v82, s4, v236
	v_exp_f32_e32 v82, v82
	v_med3_f32 v83, v83, s4, v236
	v_exp_f32_e32 v83, v83
	v_mfma_f32_32x32x16_bf16 v[184:199], v[168:171], v[108:111], v[184:199]
	v_med3_f32 v84, v84, s4, v236
	v_exp_f32_e32 v84, v84
	v_med3_f32 v85, v85, s4, v236
	v_exp_f32_e32 v85, v85
	v_mfma_f32_32x32x16_bf16 v[184:199], v[172:175], v[104:107], v[184:199]
	v_med3_f32 v86, v86, s4, v236
	v_exp_f32_e32 v86, v86
	v_med3_f32 v87, v87, s4, v236
	v_exp_f32_e32 v87, v87
	ds_read_b128 v[160:163], v15 offset:24576
	ds_read_b128 v[164:167], v15 offset:28672
	ds_read_b128 v[168:171], v15 offset:32768
	ds_read_b128 v[172:175], v15 offset:36864
	s_waitcnt lgkmcnt(8)
	v_mfma_f32_32x32x16_bf16 v[184:199], v[2:5], v[100:103], v[184:199]
	v_med3_f32 v88, v88, s4, v236
	v_exp_f32_e32 v88, v88
	v_med3_f32 v89, v89, s4, v236
	v_exp_f32_e32 v89, v89
	v_add_f32_e32 v200, v80, v81
	v_add_f32_e32 v200, v200, v82
	v_mfma_f32_32x32x16_bf16 v[184:199], v[6:9], v[140:143], v[184:199]
	v_med3_f32 v90, v90, s4, v236
	v_exp_f32_e32 v90, v90
	v_med3_f32 v91, v91, s4, v236
	v_exp_f32_e32 v91, v91
	v_add_f32_e32 v200, v200, v83
	v_add_f32_e32 v200, v200, v84
	v_mfma_f32_32x32x16_bf16 v[184:199], v[10:13], v[96:99], v[184:199]
	v_med3_f32 v92, v92, s4, v236
	v_exp_f32_e32 v92, v92
	v_med3_f32 v93, v93, s4, v236
	v_exp_f32_e32 v93, v93
	v_add_f32_e32 v200, v200, v85
	v_add_f32_e32 v200, v200, v86
	v_mfma_f32_32x32x16_bf16 v[184:199], v[238:241], v[136:139], v[184:199]
	v_med3_f32 v94, v94, s4, v236
	v_exp_f32_e32 v94, v94
	v_med3_f32 v95, v95, s4, v236
	v_exp_f32_e32 v95, v95
	v_add_f32_e32 v200, v200, v87
	s_setprio 1
	ds_read_b128 v[2:5], v176 offset:24576
	ds_read_b128 v[6:9], v176 offset:28672
	ds_read_b128 v[10:13], v176 offset:32768
	ds_read_b128 v[238:241], v176 offset:36864
	v_cvt_pk_bf16_f32 v80, v80, v81
	v_cvt_pk_bf16_f32 v81, v82, v83
	v_cvt_pk_bf16_f32 v82, v84, v85
	v_cvt_pk_bf16_f32 v83, v86, v87
	v_add_f32_e32 v200, v200, v88
	v_add_f32_e32 v200, v200, v89
	s_waitcnt lgkmcnt(8)
	v_mfma_f32_32x32x16_bf16 v[64:79], v[80:83], v[144:147], v[64:79]
	v_med3_f32 v184, v184, s4, v236
	v_exp_f32_e32 v184, v184
	v_med3_f32 v185, v185, s4, v236
	v_exp_f32_e32 v185, v185
	v_add_f32_e32 v200, v200, v90
	v_add_f32_e32 v200, v200, v91
	v_mfma_f32_32x32x16_bf16 v[48:63], v[80:83], v[148:151], v[48:63]
	v_med3_f32 v186, v186, s4, v236
	v_exp_f32_e32 v186, v186
	v_med3_f32 v187, v187, s4, v236
	v_exp_f32_e32 v187, v187
	v_add_f32_e32 v200, v200, v92
	v_add_f32_e32 v200, v200, v93
	v_mfma_f32_32x32x16_bf16 v[32:47], v[80:83], v[152:155], v[32:47]
	v_med3_f32 v188, v188, s4, v236
	v_exp_f32_e32 v188, v188
	v_med3_f32 v189, v189, s4, v236
	v_exp_f32_e32 v189, v189
	v_add_f32_e32 v200, v200, v94
	v_add_f32_e32 v200, v200, v95
	v_mfma_f32_32x32x16_bf16 v[16:31], v[80:83], v[156:159], v[16:31]
	v_med3_f32 v190, v190, s4, v236
	v_exp_f32_e32 v190, v190
	v_med3_f32 v191, v191, s4, v236
	v_exp_f32_e32 v191, v191
	v_cvt_pk_bf16_f32 v84, v88, v89
	v_cvt_pk_bf16_f32 v85, v90, v91
	v_cvt_pk_bf16_f32 v86, v92, v93
	v_cvt_pk_bf16_f32 v87, v94, v95
	ds_read_b128 v[144:147], v177 offset:24576
	ds_read_b128 v[148:151], v177 offset:28672
	ds_read_b128 v[152:155], v177 offset:32768
	ds_read_b128 v[156:159], v177 offset:36864
	s_waitcnt lgkmcnt(8)
	v_mfma_f32_32x32x16_bf16 v[64:79], v[84:87], v[160:163], v[64:79]
	v_med3_f32 v192, v192, s4, v236
	v_exp_f32_e32 v192, v192
	v_med3_f32 v193, v193, s4, v236
	v_exp_f32_e32 v193, v193
	v_add_f32_e32 v201, v184, v185
	v_add_f32_e32 v201, v201, v186
	v_mfma_f32_32x32x16_bf16 v[48:63], v[84:87], v[164:167], v[48:63]
	v_med3_f32 v194, v194, s4, v236
	v_exp_f32_e32 v194, v194
	v_med3_f32 v195, v195, s4, v236
	v_exp_f32_e32 v195, v195
	v_add_f32_e32 v201, v201, v187
	v_add_f32_e32 v201, v201, v188
	v_mfma_f32_32x32x16_bf16 v[32:47], v[84:87], v[168:171], v[32:47]
	v_med3_f32 v196, v196, s4, v236
	v_exp_f32_e32 v196, v196
	v_med3_f32 v197, v197, s4, v236
	v_exp_f32_e32 v197, v197
	v_add_f32_e32 v201, v201, v189
	v_mfma_f32_32x32x16_bf16 v[16:31], v[84:87], v[172:175], v[16:31]
	v_med3_f32 v198, v198, s4, v236
	v_exp_f32_e32 v198, v198
	v_med3_f32 v199, v199, s4, v236
	v_exp_f32_e32 v199, v199
	v_add_f32_e32 v201, v201, v190
	v_cvt_pk_bf16_f32 v184, v184, v185
	v_cvt_pk_bf16_f32 v185, v186, v187
	v_cvt_pk_bf16_f32 v186, v188, v189
	v_cvt_pk_bf16_f32 v187, v190, v191
	v_add_f32_e32 v201, v201, v191
	s_setprio 0
	s_waitcnt lgkmcnt(4)
	v_mfma_f32_32x32x16_bf16 v[64:79], v[184:187], v[2:5], v[64:79]
	v_add_f32_e32 v201, v201, v192
	v_add_f32_e32 v201, v201, v193
	v_add_f32_e32 v201, v201, v194
	v_mfma_f32_32x32x16_bf16 v[48:63], v[184:187], v[6:9], v[48:63]
	v_add_f32_e32 v201, v201, v195
	v_add_f32_e32 v201, v201, v196
	v_add_f32_e32 v201, v201, v197
	v_mfma_f32_32x32x16_bf16 v[32:47], v[184:187], v[10:13], v[32:47]
	v_add_f32_e32 v201, v201, v198
	v_add_f32_e32 v201, v201, v199
	v_cvt_pk_bf16_f32 v188, v192, v193
	v_cvt_pk_bf16_f32 v189, v194, v195
	v_cvt_pk_bf16_f32 v190, v196, v197
	v_cvt_pk_bf16_f32 v191, v198, v199
	v_mfma_f32_32x32x16_bf16 v[16:31], v[184:187], v[238:241], v[16:31]
	v_add_f32_e32 v200, v200, v201
	v_add_f32_e32 v218, v218, v200
	s_waitcnt lgkmcnt(0)
	v_mfma_f32_32x32x16_bf16 v[64:79], v[188:191], v[144:147], v[64:79]
	v_mfma_f32_32x32x16_bf16 v[48:63], v[188:191], v[148:151], v[48:63]
	v_mfma_f32_32x32x16_bf16 v[32:47], v[188:191], v[152:155], v[32:47]
	v_mfma_f32_32x32x16_bf16 v[16:31], v[188:191], v[156:159], v[16:31]
	s_waitcnt vmcnt(0) lgkmcnt(0)
	s_branch .LBB0_530

.LBB0_573:
	s_add_i32 s10, s28, 1
	s_cmp_lg_u32 s28, 2
	s_cselect_b32 s28, s10, 0
	s_add_i32 s10, s7, 1
	s_cmp_lg_u32 s7, 2
	s_cselect_b32 s7, s10, 0
	s_add_i32 s33, s33, 1
	s_add_i32 s86, s86, 64
	s_mul_i32 s100, s28, 0xa000
	s_add_i32 s10, s33, 2
	s_cmp_ge_i32 s10, s21
	s_cselect_b64 s[22:23], -1, 0
	s_cmp_gt_i32 s33, s9
	s_cselect_b64 s[34:35], -1, 0
	s_and_b64 vcc, exec, s[34:35]
	s_cmp_eq_u32 s21, s33
	s_barrier
.Lat2_dispatch:
	s_cbranch_scc1 .LBB0_583
	s_cbranch_vccnz .Lat2_skip
	s_and_b64 vcc, exec, s[22:23]
	s_cbranch_vccnz .Lat2_nodma
	s_setprio 3
	v_add_u32_e32 v198, s100, v218
	v_add_u32_e32 v199, s100, v219
	v_add_u32_e32 v200, s100, v209
	v_add_u32_e32 v201, s100, v208
	ds_read_b128 v[130:133], v198 offset:0
	ds_read_b128 v[134:137], v199 offset:0
	ds_read_b128 v[138:141], v200 offset:0
	ds_read_b128 v[142:145], v201 offset:0
	ds_read_b128 v[146:149], v198 offset:8192
	ds_read_b128 v[150:153], v199 offset:8192
	ds_read_b128 v[154:157], v200 offset:8192
	ds_read_b128 v[158:161], v201 offset:8192
	ds_read_b128 v[162:165], v198 offset:16384
	ds_read_b128 v[166:169], v199 offset:16384
	ds_read_b128 v[170:173], v200 offset:16384
	ds_read_b128 v[176:179], v201 offset:16384
	s_waitcnt lgkmcnt(8)
	v_mfma_f32_32x32x16_bf16 v[66:81], v[130:133], v[118:121], 0
	v_mfma_f32_32x32x16_bf16 v[66:81], v[134:137], v[114:117], v[66:81]
	v_mfma_f32_32x32x16_bf16 v[66:81], v[138:141], v[110:113], v[66:81]
	v_mfma_f32_32x32x16_bf16 v[66:81], v[142:145], v[106:109], v[66:81]
	ds_read_b128 v[130:133], v198 offset:4096
	ds_read_b128 v[134:137], v199 offset:4096
	ds_read_b128 v[138:141], v200 offset:4096
	ds_read_b128 v[142:145], v201 offset:4096
	s_waitcnt lgkmcnt(8)
	v_mfma_f32_32x32x16_bf16 v[66:81], v[146:149], v[102:105], v[66:81]
	v_mfma_f32_32x32x16_bf16 v[66:81], v[150:153], v[98:101], v[66:81]
	v_mfma_f32_32x32x16_bf16 v[66:81], v[154:157], v[94:97], v[66:81]
	v_mfma_f32_32x32x16_bf16 v[66:81], v[158:161], v[90:93], v[66:81]
	ds_read_b128 v[146:149], v198 offset:12288
	ds_read_b128 v[150:153], v199 offset:12288
	ds_read_b128 v[154:157], v200 offset:12288
	ds_read_b128 v[158:161], v201 offset:12288
	s_waitcnt lgkmcnt(8)
	v_mfma_f32_32x32x16_bf16 v[66:81], v[162:165], v[86:89], v[66:81]
	v_mfma_f32_32x32x16_bf16 v[66:81], v[166:169], v[126:129], v[66:81]
	v_mfma_f32_32x32x16_bf16 v[66:81], v[170:173], v[82:85], v[66:81]
	v_mfma_f32_32x32x16_bf16 v[66:81], v[176:179], v[122:125], v[66:81]
	s_setprio 2
	ds_read_b128 v[162:165], v198 offset:20480
	ds_read_b128 v[166:169], v199 offset:20480
	ds_read_b128 v[170:173], v200 offset:20480
	ds_read_b128 v[176:179], v201 offset:20480
	s_waitcnt lgkmcnt(8)
	v_mfma_f32_32x32x16_bf16 v[182:197], v[130:133], v[118:121], 0
	v_mfma_f32_32x32x16_bf16 v[182:197], v[134:137], v[114:117], v[182:197]
	v_mfma_f32_32x32x16_bf16 v[182:197], v[138:141], v[110:113], v[182:197]
	v_mfma_f32_32x32x16_bf16 v[182:197], v[142:145], v[106:109], v[182:197]
	ds_read_b128 v[130:133], v198 offset:24576
	ds_read_b128 v[134:137], v198 offset:28672
	ds_read_b128 v[138:141], v198 offset:32768
	ds_read_b128 v[142:145], v198 offset:36864
	s_waitcnt lgkmcnt(8)
	v_mfma_f32_32x32x16_bf16 v[182:197], v[146:149], v[102:105], v[182:197]
	v_med3_f32 v66, v66, s4, v236
	v_exp_f32_e32 v66, v66
	v_med3_f32 v67, v67, s4, v236
	v_exp_f32_e32 v67, v67
	v_mfma_f32_32x32x16_bf16 v[182:197], v[150:153], v[98:101], v[182:197]
	v_med3_f32 v68, v68, s4, v236
	v_exp_f32_e32 v68, v68
	v_med3_f32 v69, v69, s4, v236
	v_exp_f32_e32 v69, v69
	v_mfma_f32_32x32x16_bf16 v[182:197], v[154:157], v[94:97], v[182:197]
	v_med3_f32 v70, v70, s4, v236
	v_exp_f32_e32 v70, v70
	v_med3_f32 v71, v71, s4, v236
	v_exp_f32_e32 v71, v71
	v_mfma_f32_32x32x16_bf16 v[182:197], v[158:161], v[90:93], v[182:197]
	v_med3_f32 v72, v72, s4, v236
	v_exp_f32_e32 v72, v72
	v_med3_f32 v73, v73, s4, v236
	v_exp_f32_e32 v73, v73
	ds_read_b128 v[146:149], v199 offset:24576
	ds_read_b128 v[150:153], v199 offset:28672
	ds_read_b128 v[154:157], v199 offset:32768
	ds_read_b128 v[158:161], v199 offset:36864
	s_waitcnt lgkmcnt(8)
	v_mfma_f32_32x32x16_bf16 v[182:197], v[162:165], v[86:89], v[182:197]
	v_med3_f32 v74, v74, s4, v236
	v_exp_f32_e32 v74, v74
	v_med3_f32 v75, v75, s4, v236
	v_exp_f32_e32 v75, v75
	v_add_f32_e32 v202, v66, v67
	v_add_f32_e32 v202, v202, v68
	v_mfma_f32_32x32x16_bf16 v[182:197], v[166:169], v[126:129], v[182:197]
	v_med3_f32 v76, v76, s4, v236
	v_exp_f32_e32 v76, v76
	v_med3_f32 v77, v77, s4, v236
	v_exp_f32_e32 v77, v77
	v_add_f32_e32 v202, v202, v69
	v_add_f32_e32 v202, v202, v70
	v_mfma_f32_32x32x16_bf16 v[182:197], v[170:173], v[82:85], v[182:197]
	v_med3_f32 v78, v78, s4, v236
	v_exp_f32_e32 v78, v78
	v_med3_f32 v79, v79, s4, v236
	v_exp_f32_e32 v79, v79
	v_add_f32_e32 v202, v202, v71
	v_add_f32_e32 v202, v202, v72
	v_mfma_f32_32x32x16_bf16 v[182:197], v[176:179], v[122:125], v[182:197]
	v_med3_f32 v80, v80, s4, v236
	v_exp_f32_e32 v80, v80
	v_med3_f32 v81, v81, s4, v236
	v_exp_f32_e32 v81, v81
	v_add_f32_e32 v202, v202, v73
	s_setprio 1
	ds_read_b128 v[162:165], v200 offset:24576
	ds_read_b128 v[166:169], v200 offset:28672
	ds_read_b128 v[170:173], v200 offset:32768
	ds_read_b128 v[176:179], v200 offset:36864
	v_cvt_pk_bf16_f32 v66, v66, v67
	v_cvt_pk_bf16_f32 v67, v68, v69
	v_cvt_pk_bf16_f32 v68, v70, v71
	v_cvt_pk_bf16_f32 v69, v72, v73
	v_add_f32_e32 v202, v202, v74
	v_add_f32_e32 v202, v202, v75
	s_waitcnt lgkmcnt(8)
	v_mfma_f32_32x32x16_bf16 v[50:65], v[66:69], v[130:133], v[50:65]
	v_med3_f32 v182, v182, s4, v236
	v_exp_f32_e32 v182, v182
	v_med3_f32 v183, v183, s4, v236
	v_exp_f32_e32 v183, v183
	v_add_f32_e32 v202, v202, v76
	v_add_f32_e32 v202, v202, v77
	v_mfma_f32_32x32x16_bf16 v[34:49], v[66:69], v[134:137], v[34:49]
	v_med3_f32 v184, v184, s4, v236
	v_exp_f32_e32 v184, v184
	v_med3_f32 v185, v185, s4, v236
	v_exp_f32_e32 v185, v185
	v_add_f32_e32 v202, v202, v78
	v_add_f32_e32 v202, v202, v79
	v_mfma_f32_32x32x16_bf16 v[18:33], v[66:69], v[138:141], v[18:33]
	v_med3_f32 v186, v186, s4, v236
	v_exp_f32_e32 v186, v186
	v_med3_f32 v187, v187, s4, v236
	v_exp_f32_e32 v187, v187
	v_add_f32_e32 v202, v202, v80
	v_add_f32_e32 v202, v202, v81
	v_mfma_f32_32x32x16_bf16 v[2:17], v[66:69], v[142:145], v[2:17]
	v_med3_f32 v188, v188, s4, v236
	v_exp_f32_e32 v188, v188
	v_med3_f32 v189, v189, s4, v236
	v_exp_f32_e32 v189, v189
	v_cvt_pk_bf16_f32 v70, v74, v75
	v_cvt_pk_bf16_f32 v71, v76, v77
	v_cvt_pk_bf16_f32 v72, v78, v79
	v_cvt_pk_bf16_f32 v73, v80, v81
	ds_read_b128 v[130:133], v201 offset:24576
	ds_read_b128 v[134:137], v201 offset:28672
	ds_read_b128 v[138:141], v201 offset:32768
	ds_read_b128 v[142:145], v201 offset:36864
	s_waitcnt lgkmcnt(8)
	v_mfma_f32_32x32x16_bf16 v[50:65], v[70:73], v[146:149], v[50:65]
	v_med3_f32 v190, v190, s4, v236
	v_exp_f32_e32 v190, v190
	v_med3_f32 v191, v191, s4, v236
	v_exp_f32_e32 v191, v191
	v_add_f32_e32 v203, v182, v183
	v_add_f32_e32 v203, v203, v184
	v_mfma_f32_32x32x16_bf16 v[34:49], v[70:73], v[150:153], v[34:49]
	v_med3_f32 v192, v192, s4, v236
	v_exp_f32_e32 v192, v192
	v_med3_f32 v193, v193, s4, v236
	v_exp_f32_e32 v193, v193
	v_add_f32_e32 v203, v203, v185
	v_add_f32_e32 v203, v203, v186
	v_mfma_f32_32x32x16_bf16 v[18:33], v[70:73], v[154:157], v[18:33]
	v_med3_f32 v194, v194, s4, v236
	v_exp_f32_e32 v194, v194
	v_med3_f32 v195, v195, s4, v236
	v_exp_f32_e32 v195, v195
	v_add_f32_e32 v203, v203, v187
	v_mfma_f32_32x32x16_bf16 v[2:17], v[70:73], v[158:161], v[2:17]
	v_med3_f32 v196, v196, s4, v236
	v_exp_f32_e32 v196, v196
	v_med3_f32 v197, v197, s4, v236
	v_exp_f32_e32 v197, v197
	v_add_f32_e32 v203, v203, v188
	v_cvt_pk_bf16_f32 v182, v182, v183
	v_cvt_pk_bf16_f32 v183, v184, v185
	v_cvt_pk_bf16_f32 v184, v186, v187
	v_cvt_pk_bf16_f32 v185, v188, v189
	v_add_f32_e32 v203, v203, v189
	s_setprio 0
	s_waitcnt lgkmcnt(4)
	v_mfma_f32_32x32x16_bf16 v[50:65], v[182:185], v[162:165], v[50:65]
	v_mad_u64_u32 v[204:205], s[10:11], s86, v228, v[174:175]
	s_mul_i32 s10, s7, 0xa000
	s_add_i32 s10, s0, s10
	s_mov_b32 m0, s10
	v_lshl_add_u64 v[206:207], v[204:205], 0, s[94:95]
	global_load_lds_dwordx4 v[204:205], off
	v_add_f32_e32 v203, v203, v190
	v_add_f32_e32 v203, v203, v191
	v_add_f32_e32 v203, v203, v192
	v_mfma_f32_32x32x16_bf16 v[34:49], v[182:185], v[166:169], v[34:49]
	s_add_i32 m0, s10, 0x2000
	v_lshl_add_u64 v[204:205], v[204:205], 0, s[96:97]
	global_load_lds_dwordx4 v[206:207], off
	v_add_f32_e32 v203, v203, v193
	v_add_f32_e32 v203, v203, v194
	v_add_f32_e32 v203, v203, v195
	v_mfma_f32_32x32x16_bf16 v[18:33], v[182:185], v[170:173], v[18:33]
	s_add_i32 m0, s10, 0x4000
	s_nop 0
	global_load_lds_dwordx4 v[204:205], off
	v_lshl_add_u64 v[204:205], s[86:87], 1, v[180:181]
	s_add_i32 m0, s10, 0x6000
	v_add_f32_e32 v203, v203, v196
	v_add_f32_e32 v203, v203, v197
	v_cvt_pk_bf16_f32 v186, v190, v191
	v_cvt_pk_bf16_f32 v187, v192, v193
	v_cvt_pk_bf16_f32 v188, v194, v195
	v_cvt_pk_bf16_f32 v189, v196, v197
	v_mfma_f32_32x32x16_bf16 v[2:17], v[182:185], v[176:179], v[2:17]
	global_load_lds_dwordx4 v[204:205], off
	v_lshl_add_u64 v[204:205], v[204:205], 0, s[92:93]
	s_add_i32 m0, s10, 0x8000
	v_add_f32_e32 v202, v202, v203
	v_add_f32_e32 v0, v0, v202
	s_waitcnt lgkmcnt(0)
	v_mfma_f32_32x32x16_bf16 v[50:65], v[186:189], v[130:133], v[50:65]
	global_load_lds_dwordx4 v[204:205], off
	v_mfma_f32_32x32x16_bf16 v[34:49], v[186:189], v[134:137], v[34:49]
	v_mfma_f32_32x32x16_bf16 v[18:33], v[186:189], v[138:141], v[18:33]
	v_mfma_f32_32x32x16_bf16 v[2:17], v[186:189], v[142:145], v[2:17]
	s_waitcnt vmcnt(5) lgkmcnt(0)
	s_branch .LBB0_573
.LBB0_574:
	s_mul_i32 s100, s28, 0xa000
	s_add_i32 s10, s33, 2
	s_cmp_ge_i32 s10, s21
	s_cselect_b64 s[22:23], -1, 0
	s_cmp_gt_i32 s33, s9
	s_cselect_b64 s[34:35], -1, 0
	s_and_b64 vcc, exec, s[34:35]
	s_cmp_eq_u32 s21, s33
	s_branch .Lat2_dispatch
.Lat2_nodma:
	s_setprio 3
	v_add_u32_e32 v198, s100, v218
	v_add_u32_e32 v199, s100, v219
	v_add_u32_e32 v200, s100, v209
	v_add_u32_e32 v201, s100, v208
	ds_read_b128 v[130:133], v198 offset:0
	ds_read_b128 v[134:137], v199 offset:0
	ds_read_b128 v[138:141], v200 offset:0
	ds_read_b128 v[142:145], v201 offset:0
	ds_read_b128 v[146:149], v198 offset:8192
	ds_read_b128 v[150:153], v199 offset:8192
	ds_read_b128 v[154:157], v200 offset:8192
	ds_read_b128 v[158:161], v201 offset:8192
	ds_read_b128 v[162:165], v198 offset:16384
	ds_read_b128 v[166:169], v199 offset:16384
	ds_read_b128 v[170:173], v200 offset:16384
	ds_read_b128 v[176:179], v201 offset:16384
	s_waitcnt lgkmcnt(8)
	v_mfma_f32_32x32x16_bf16 v[66:81], v[130:133], v[118:121], 0
	v_mfma_f32_32x32x16_bf16 v[66:81], v[134:137], v[114:117], v[66:81]
	v_mfma_f32_32x32x16_bf16 v[66:81], v[138:141], v[110:113], v[66:81]
	v_mfma_f32_32x32x16_bf16 v[66:81], v[142:145], v[106:109], v[66:81]
	ds_read_b128 v[130:133], v198 offset:4096
	ds_read_b128 v[134:137], v199 offset:4096
	ds_read_b128 v[138:141], v200 offset:4096
	ds_read_b128 v[142:145], v201 offset:4096
	s_waitcnt lgkmcnt(8)
	v_mfma_f32_32x32x16_bf16 v[66:81], v[146:149], v[102:105], v[66:81]
	v_mfma_f32_32x32x16_bf16 v[66:81], v[150:153], v[98:101], v[66:81]
	v_mfma_f32_32x32x16_bf16 v[66:81], v[154:157], v[94:97], v[66:81]
	v_mfma_f32_32x32x16_bf16 v[66:81], v[158:161], v[90:93], v[66:81]
	ds_read_b128 v[146:149], v198 offset:12288
	ds_read_b128 v[150:153], v199 offset:12288
	ds_read_b128 v[154:157], v200 offset:12288
	ds_read_b128 v[158:161], v201 offset:12288
	s_waitcnt lgkmcnt(8)
	v_mfma_f32_32x32x16_bf16 v[66:81], v[162:165], v[86:89], v[66:81]
	v_mfma_f32_32x32x16_bf16 v[66:81], v[166:169], v[126:129], v[66:81]
	v_mfma_f32_32x32x16_bf16 v[66:81], v[170:173], v[82:85], v[66:81]
	v_mfma_f32_32x32x16_bf16 v[66:81], v[176:179], v[122:125], v[66:81]
	s_setprio 2
	ds_read_b128 v[162:165], v198 offset:20480
	ds_read_b128 v[166:169], v199 offset:20480
	ds_read_b128 v[170:173], v200 offset:20480
	ds_read_b128 v[176:179], v201 offset:20480
	s_waitcnt lgkmcnt(8)
	v_mfma_f32_32x32x16_bf16 v[182:197], v[130:133], v[118:121], 0
	v_mfma_f32_32x32x16_bf16 v[182:197], v[134:137], v[114:117], v[182:197]
	v_mfma_f32_32x32x16_bf16 v[182:197], v[138:141], v[110:113], v[182:197]
	v_mfma_f32_32x32x16_bf16 v[182:197], v[142:145], v[106:109], v[182:197]
	ds_read_b128 v[130:133], v198 offset:24576
	ds_read_b128 v[134:137], v198 offset:28672
	ds_read_b128 v[138:141], v198 offset:32768
	ds_read_b128 v[142:145], v198 offset:36864
	s_waitcnt lgkmcnt(8)
	v_mfma_f32_32x32x16_bf16 v[182:197], v[146:149], v[102:105], v[182:197]
	v_med3_f32 v66, v66, s4, v236
	v_exp_f32_e32 v66, v66
	v_med3_f32 v67, v67, s4, v236
	v_exp_f32_e32 v67, v67
	v_mfma_f32_32x32x16_bf16 v[182:197], v[150:153], v[98:101], v[182:197]
	v_med3_f32 v68, v68, s4, v236
	v_exp_f32_e32 v68, v68
	v_med3_f32 v69, v69, s4, v236
	v_exp_f32_e32 v69, v69
	v_mfma_f32_32x32x16_bf16 v[182:197], v[154:157], v[94:97], v[182:197]
	v_med3_f32 v70, v70, s4, v236
	v_exp_f32_e32 v70, v70
	v_med3_f32 v71, v71, s4, v236
	v_exp_f32_e32 v71, v71
	v_mfma_f32_32x32x16_bf16 v[182:197], v[158:161], v[90:93], v[182:197]
	v_med3_f32 v72, v72, s4, v236
	v_exp_f32_e32 v72, v72
	v_med3_f32 v73, v73, s4, v236
	v_exp_f32_e32 v73, v73
	ds_read_b128 v[146:149], v199 offset:24576
	ds_read_b128 v[150:153], v199 offset:28672
	ds_read_b128 v[154:157], v199 offset:32768
	ds_read_b128 v[158:161], v199 offset:36864
	s_waitcnt lgkmcnt(8)
	v_mfma_f32_32x32x16_bf16 v[182:197], v[162:165], v[86:89], v[182:197]
	v_med3_f32 v74, v74, s4, v236
	v_exp_f32_e32 v74, v74
	v_med3_f32 v75, v75, s4, v236
	v_exp_f32_e32 v75, v75
	v_add_f32_e32 v202, v66, v67
	v_add_f32_e32 v202, v202, v68
	v_mfma_f32_32x32x16_bf16 v[182:197], v[166:169], v[126:129], v[182:197]
	v_med3_f32 v76, v76, s4, v236
	v_exp_f32_e32 v76, v76
	v_med3_f32 v77, v77, s4, v236
	v_exp_f32_e32 v77, v77
	v_add_f32_e32 v202, v202, v69
	v_add_f32_e32 v202, v202, v70
	v_mfma_f32_32x32x16_bf16 v[182:197], v[170:173], v[82:85], v[182:197]
	v_med3_f32 v78, v78, s4, v236
	v_exp_f32_e32 v78, v78
	v_med3_f32 v79, v79, s4, v236
	v_exp_f32_e32 v79, v79
	v_add_f32_e32 v202, v202, v71
	v_add_f32_e32 v202, v202, v72
	v_mfma_f32_32x32x16_bf16 v[182:197], v[176:179], v[122:125], v[182:197]
	v_med3_f32 v80, v80, s4, v236
	v_exp_f32_e32 v80, v80
	v_med3_f32 v81, v81, s4, v236
	v_exp_f32_e32 v81, v81
	v_add_f32_e32 v202, v202, v73
	s_setprio 1
	ds_read_b128 v[162:165], v200 offset:24576
	ds_read_b128 v[166:169], v200 offset:28672
	ds_read_b128 v[170:173], v200 offset:32768
	ds_read_b128 v[176:179], v200 offset:36864
	v_cvt_pk_bf16_f32 v66, v66, v67
	v_cvt_pk_bf16_f32 v67, v68, v69
	v_cvt_pk_bf16_f32 v68, v70, v71
	v_cvt_pk_bf16_f32 v69, v72, v73
	v_add_f32_e32 v202, v202, v74
	v_add_f32_e32 v202, v202, v75
	s_waitcnt lgkmcnt(8)
	v_mfma_f32_32x32x16_bf16 v[50:65], v[66:69], v[130:133], v[50:65]
	v_med3_f32 v182, v182, s4, v236
	v_exp_f32_e32 v182, v182
	v_med3_f32 v183, v183, s4, v236
	v_exp_f32_e32 v183, v183
	v_add_f32_e32 v202, v202, v76
	v_add_f32_e32 v202, v202, v77
	v_mfma_f32_32x32x16_bf16 v[34:49], v[66:69], v[134:137], v[34:49]
	v_med3_f32 v184, v184, s4, v236
	v_exp_f32_e32 v184, v184
	v_med3_f32 v185, v185, s4, v236
	v_exp_f32_e32 v185, v185
	v_add_f32_e32 v202, v202, v78
	v_add_f32_e32 v202, v202, v79
	v_mfma_f32_32x32x16_bf16 v[18:33], v[66:69], v[138:141], v[18:33]
	v_med3_f32 v186, v186, s4, v236
	v_exp_f32_e32 v186, v186
	v_med3_f32 v187, v187, s4, v236
	v_exp_f32_e32 v187, v187
	v_add_f32_e32 v202, v202, v80
	v_add_f32_e32 v202, v202, v81
	v_mfma_f32_32x32x16_bf16 v[2:17], v[66:69], v[142:145], v[2:17]
	v_med3_f32 v188, v188, s4, v236
	v_exp_f32_e32 v188, v188
	v_med3_f32 v189, v189, s4, v236
	v_exp_f32_e32 v189, v189
	v_cvt_pk_bf16_f32 v70, v74, v75
	v_cvt_pk_bf16_f32 v71, v76, v77
	v_cvt_pk_bf16_f32 v72, v78, v79
	v_cvt_pk_bf16_f32 v73, v80, v81
	ds_read_b128 v[130:133], v201 offset:24576
	ds_read_b128 v[134:137], v201 offset:28672
	ds_read_b128 v[138:141], v201 offset:32768
	ds_read_b128 v[142:145], v201 offset:36864
	s_waitcnt lgkmcnt(8)
	v_mfma_f32_32x32x16_bf16 v[50:65], v[70:73], v[146:149], v[50:65]
	v_med3_f32 v190, v190, s4, v236
	v_exp_f32_e32 v190, v190
	v_med3_f32 v191, v191, s4, v236
	v_exp_f32_e32 v191, v191
	v_add_f32_e32 v203, v182, v183
	v_add_f32_e32 v203, v203, v184
	v_mfma_f32_32x32x16_bf16 v[34:49], v[70:73], v[150:153], v[34:49]
	v_med3_f32 v192, v192, s4, v236
	v_exp_f32_e32 v192, v192
	v_med3_f32 v193, v193, s4, v236
	v_exp_f32_e32 v193, v193
	v_add_f32_e32 v203, v203, v185
	v_add_f32_e32 v203, v203, v186
	v_mfma_f32_32x32x16_bf16 v[18:33], v[70:73], v[154:157], v[18:33]
	v_med3_f32 v194, v194, s4, v236
	v_exp_f32_e32 v194, v194
	v_med3_f32 v195, v195, s4, v236
	v_exp_f32_e32 v195, v195
	v_add_f32_e32 v203, v203, v187
	v_mfma_f32_32x32x16_bf16 v[2:17], v[70:73], v[158:161], v[2:17]
	v_med3_f32 v196, v196, s4, v236
	v_exp_f32_e32 v196, v196
	v_med3_f32 v197, v197, s4, v236
	v_exp_f32_e32 v197, v197
	v_add_f32_e32 v203, v203, v188
	v_cvt_pk_bf16_f32 v182, v182, v183
	v_cvt_pk_bf16_f32 v183, v184, v185
	v_cvt_pk_bf16_f32 v184, v186, v187
	v_cvt_pk_bf16_f32 v185, v188, v189
	v_add_f32_e32 v203, v203, v189
	s_setprio 0
	s_waitcnt lgkmcnt(4)
	v_mfma_f32_32x32x16_bf16 v[50:65], v[182:185], v[162:165], v[50:65]
	v_add_f32_e32 v203, v203, v190
	v_add_f32_e32 v203, v203, v191
	v_add_f32_e32 v203, v203, v192
	v_mfma_f32_32x32x16_bf16 v[34:49], v[182:185], v[166:169], v[34:49]
	v_add_f32_e32 v203, v203, v193
	v_add_f32_e32 v203, v203, v194
	v_add_f32_e32 v203, v203, v195
	v_mfma_f32_32x32x16_bf16 v[18:33], v[182:185], v[170:173], v[18:33]
	v_add_f32_e32 v203, v203, v196
	v_add_f32_e32 v203, v203, v197
	v_cvt_pk_bf16_f32 v186, v190, v191
	v_cvt_pk_bf16_f32 v187, v192, v193
	v_cvt_pk_bf16_f32 v188, v194, v195
	v_cvt_pk_bf16_f32 v189, v196, v197
	v_mfma_f32_32x32x16_bf16 v[2:17], v[182:185], v[176:179], v[2:17]
	v_add_f32_e32 v202, v202, v203
	v_add_f32_e32 v0, v0, v202
	s_waitcnt lgkmcnt(0)
	v_mfma_f32_32x32x16_bf16 v[50:65], v[186:189], v[130:133], v[50:65]
	v_mfma_f32_32x32x16_bf16 v[34:49], v[186:189], v[134:137], v[34:49]
	v_mfma_f32_32x32x16_bf16 v[18:33], v[186:189], v[138:141], v[18:33]
	v_mfma_f32_32x32x16_bf16 v[2:17], v[186:189], v[142:145], v[2:17]
	s_waitcnt vmcnt(0) lgkmcnt(0)
	s_branch .LBB0_573
